# static s_setprio 1 for waves 4-7 across the attention tile loop
# baseline (speedup 1.0000x reference)
.LBB0_178:
	s_setprio 0
	v_add3_u32 v32, s13, v32, v121
	ds_read_b128 v[4:7], v32
	ds_read_b128 v[70:73], v32 offset:64
	ds_read_b128 v[74:77], v32 offset:6656
	ds_read_b128 v[86:89], v32 offset:6720
	ds_read_b128 v[90:93], v32 offset:3328
	ds_read_b128 v[94:97], v32 offset:128
	ds_read_b128 v[98:101], v32 offset:3392
	ds_read_b128 v[102:105], v32 offset:3456
	ds_read_b128 v[106:109], v32 offset:9984
	ds_read_b128 v[120:123], v32 offset:6784
	ds_read_b128 v[124:127], v32 offset:10048
	ds_read_b128 v[128:131], v32 offset:10112
	s_addk_i32 s13, 0x3400
	s_waitcnt lgkmcnt(11)
	v_mfma_f32_16x16x32_bf16 v[132:135], v[4:7], v[50:53], v[62:65]
	v_add_u32_e32 v32, s13, v119
	s_waitcnt lgkmcnt(7)
	v_mfma_f32_16x16x32_bf16 v[136:139], v[90:93], v[50:53], v[62:65]
	v_mfma_f32_16x16x32_bf16 v[4:7], v[4:7], v[16:19], v[66:69]
	v_mfma_f32_16x16x32_bf16 v[90:93], v[90:93], v[16:19], v[66:69]
	v_mfma_f32_16x16x32_bf16 v[140:143], v[74:77], v[50:53], v[62:65]
	v_mfma_f32_16x16x32_bf16 v[74:77], v[74:77], v[16:19], v[66:69]
	s_waitcnt lgkmcnt(3)
	v_mfma_f32_16x16x32_bf16 v[50:53], v[106:109], v[50:53], v[62:65]
	v_mfma_f32_16x16x32_bf16 v[16:19], v[106:109], v[16:19], v[66:69]
	v_mfma_f32_16x16x32_bf16 v[62:65], v[70:73], v[46:49], v[132:135]
	v_mfma_f32_16x16x32_bf16 v[66:69], v[98:101], v[46:49], v[136:139]
	v_mfma_f32_16x16x32_bf16 v[4:7], v[70:73], v[12:15], v[4:7]
	v_mfma_f32_16x16x32_bf16 v[70:73], v[98:101], v[12:15], v[90:93]
	v_mfma_f32_16x16x32_bf16 v[74:77], v[86:89], v[12:15], v[74:77]
	s_waitcnt lgkmcnt(1)
	v_mfma_f32_16x16x32_bf16 v[12:15], v[124:127], v[12:15], v[16:19]
	v_mfma_f32_16x16x32_bf16 v[16:19], v[94:97], v[24:27], v[62:65]
	ds_read_b64_tr_b16 v[62:63], v32 offset:0
	ds_read_b64_tr_b16 v[64:65], v32 offset:0x900
	v_mfma_f32_16x16x32_bf16 v[90:93], v[86:89], v[46:49], v[140:143]
	v_mfma_f32_16x16x32_bf16 v[46:49], v[124:127], v[46:49], v[50:53]
	v_mfma_f32_16x16x32_bf16 v[50:53], v[102:105], v[24:27], v[66:69]
	ds_read_b64_tr_b16 v[66:67], v32 offset:32
	ds_read_b64_tr_b16 v[68:69], v32 offset:0x920
	ds_read_b64_tr_b16 v[86:87], v32 offset:64
	ds_read_b64_tr_b16 v[88:89], v32 offset:0x940
	v_mfma_f32_16x16x32_bf16 v[4:7], v[94:97], v[8:11], v[4:7]
	ds_read_b64_tr_b16 v[94:95], v32 offset:0x60
	ds_read_b64_tr_b16 v[96:97], v32 offset:0x960
	ds_read_b64_tr_b16 v[98:99], v32 offset:0x1200
	ds_read_b64_tr_b16 v[100:101], v32 offset:0x1b00
	v_mfma_f32_16x16x32_bf16 v[70:73], v[102:105], v[8:11], v[70:73]
	ds_read_b64_tr_b16 v[102:103], v32 offset:0x1220
	ds_read_b64_tr_b16 v[104:105], v32 offset:0x1b20
	v_mfma_f32_16x16x32_bf16 v[90:93], v[120:123], v[24:27], v[90:93]
	s_waitcnt lgkmcnt(0)
	v_mfma_f32_16x16x32_bf16 v[24:27], v[128:131], v[24:27], v[46:49]
	ds_read_b64_tr_b16 v[46:47], v32 offset:0x1240
	ds_read_b64_tr_b16 v[48:49], v32 offset:0x1b40
	ds_read_b64_tr_b16 v[106:107], v32 offset:0x1260
	ds_read_b64_tr_b16 v[108:109], v32 offset:0x1b60
	v_mfma_f32_16x16x32_bf16 v[74:77], v[120:123], v[8:11], v[74:77]
	v_mfma_f32_16x16x32_bf16 v[8:11], v[128:131], v[8:11], v[12:15]
	v_exp_f32_e32 v32, v16
	v_exp_f32_e32 v84, v17
	v_exp_f32_e32 v110, v18
	v_exp_f32_e32 v111, v19
	v_exp_f32_e32 v115, v50
	v_exp_f32_e32 v116, v51
	v_exp_f32_e32 v117, v52
	v_exp_f32_e32 v118, v53
	v_exp_f32_e32 v90, v90
	v_exp_f32_e32 v91, v91
	v_exp_f32_e32 v92, v92
	v_exp_f32_e32 v93, v93
	v_exp_f32_e32 v119, v24
	v_exp_f32_e32 v120, v25
	v_exp_f32_e32 v121, v26
	v_exp_f32_e32 v122, v27
	v_cvt_pk_bf16_f32 v12, v32, v84
	v_cvt_pk_bf16_f32 v13, v110, v111
	v_cvt_pk_bf16_f32 v14, v115, v116
	v_cvt_pk_bf16_f32 v15, v117, v118
	v_cvt_pk_bf16_f32 v16, v90, v91
	v_cvt_pk_bf16_f32 v17, v92, v93
	v_cvt_pk_bf16_f32 v18, v119, v120
	v_cvt_pk_bf16_f32 v19, v121, v122
	v_exp_f32_e32 v123, v4
	v_exp_f32_e32 v124, v5
	v_exp_f32_e32 v125, v6
	v_exp_f32_e32 v126, v7
	v_exp_f32_e32 v70, v70
	v_exp_f32_e32 v71, v71
	v_exp_f32_e32 v72, v72
	v_exp_f32_e32 v73, v73
	v_exp_f32_e32 v74, v74
	v_exp_f32_e32 v75, v75
	v_exp_f32_e32 v76, v76
	v_exp_f32_e32 v77, v77
	v_exp_f32_e32 v127, v8
	v_exp_f32_e32 v128, v9
	v_exp_f32_e32 v129, v10
	v_exp_f32_e32 v130, v11
	v_cvt_pk_bf16_f32 v4, v123, v124
	v_cvt_pk_bf16_f32 v5, v125, v126
	v_cvt_pk_bf16_f32 v6, v70, v71
	v_cvt_pk_bf16_f32 v7, v72, v73
	v_cvt_pk_bf16_f32 v50, v74, v75
	v_cvt_pk_bf16_f32 v51, v76, v77
	v_cvt_pk_bf16_f32 v52, v127, v128
	v_cvt_pk_bf16_f32 v53, v129, v130
	s_waitcnt lgkmcnt(0)
	v_mfma_f32_16x16x32_bf16 v[34:37], v[86:89], v[12:15], v[34:37]
	v_add_f32_e32 v32, 0, v32
	v_add_f32_e32 v32, v84, v32
	v_add_f32_e32 v32, v110, v32
	v_mfma_f32_16x16x32_bf16 v[8:11], v[62:65], v[12:15], v[58:61]
	v_add_f32_e32 v32, v111, v32
	v_add_f32_e32 v32, v115, v32
	v_add_f32_e32 v32, v116, v32
	v_mfma_f32_16x16x32_bf16 v[58:61], v[94:97], v[12:15], v[20:23]
	v_add_f32_e32 v32, v117, v32
	v_add_f32_e32 v32, v118, v32
	v_add_f32_e32 v32, v90, v32
	v_mfma_f32_16x16x32_bf16 v[20:23], v[46:49], v[16:19], v[34:37]
	v_add_f32_e32 v32, v91, v32
	v_add_f32_e32 v32, v92, v32
	v_add_f32_e32 v32, v93, v32
	v_add_f32_e32 v34, 0, v123
	v_add_f32_e32 v34, v124, v34
	v_add_f32_e32 v34, v125, v34
	v_add_f32_e32 v34, v126, v34
	v_add_f32_e32 v34, v70, v34
	v_add_f32_e32 v34, v71, v34
	v_add_f32_e32 v34, v72, v34
	v_add_f32_e32 v34, v73, v34
	v_add_f32_e32 v34, v74, v34
	v_add_f32_e32 v34, v75, v34
	v_add_f32_e32 v34, v76, v34
	v_add_f32_e32 v34, v77, v34
	v_add_f32_e32 v32, v119, v32
	v_mfma_f32_16x16x32_bf16 v[38:41], v[66:69], v[4:7], v[38:41]
	v_add_f32_e32 v34, v127, v34
	v_add_f32_e32 v32, v120, v32
	v_add_f32_e32 v34, v128, v34
	v_add_f32_e32 v32, v121, v32
	s_lshl_b32 s0, s7, 7
	v_add_f32_e32 v34, v129, v34
	v_add_f32_e32 v32, v122, v32
	s_add_u32 s0, s18, s0
	v_add_f32_e32 v34, v130, v34
	v_add_f32_e32 v36, v83, v32
	s_addc_u32 s1, s19, 0
	v_lshlrev_b32_e32 v32, 1, v85
	v_mfma_f32_16x16x32_bf16 v[24:27], v[62:65], v[4:7], v[54:57]
	s_barrier
	v_mfma_f32_16x16x32_bf16 v[54:57], v[86:89], v[4:7], v[28:31]
	s_add_i32 s6, s6, s5
	s_cmpk_gt_i32 s6, 0x5ff
	v_mfma_f32_16x16x32_bf16 v[28:31], v[98:101], v[16:19], v[8:11]
	v_mfma_f32_16x16x32_bf16 v[8:11], v[102:105], v[50:53], v[38:41]
	s_nop 2
	v_add_f32_e32 v38, v82, v34
	v_lshl_add_u64 v[34:35], s[0:1], 0, v[32:33]
	ds_bpermute_b32 v32, v114, v36
	v_mfma_f32_16x16x32_bf16 v[42:45], v[66:69], v[12:15], v[42:45]
	s_waitcnt lgkmcnt(0)
	v_add_f32_e32 v32, v36, v32
	ds_bpermute_b32 v36, v113, v32
	v_mfma_f32_16x16x32_bf16 v[12:15], v[98:101], v[50:53], v[24:27]
	s_waitcnt lgkmcnt(0)
	v_add_f32_e32 v32, v32, v36
	v_div_scale_f32 v36, s[0:1], v32, v32, 1.0
	v_rcp_f32_e32 v37, v36
	v_mfma_f32_16x16x32_bf16 v[24:27], v[102:105], v[16:19], v[42:45]
	v_fma_f32 v39, -v36, v37, 1.0
	v_fmac_f32_e32 v37, v39, v37
	v_div_scale_f32 v39, vcc, 1.0, v32, 1.0
	v_mul_f32_e32 v40, v39, v37
	v_fma_f32 v41, -v36, v40, v39
	v_fmac_f32_e32 v40, v41, v37
	v_fma_f32 v36, -v36, v40, v39
	v_div_fmas_f32 v36, v36, v37, v40
	v_div_fixup_f32 v32, v36, v32, 1.0
	v_pk_mul_f32 v[28:29], v[28:29], v[32:33] op_sel_hi:[1,0]
	v_pk_mul_f32 v[30:31], v[30:31], v[32:33] op_sel_hi:[1,0]
	v_bfe_u32 v39, v28, 16, 1
	v_add3_u32 v28, v28, v39, s4
	v_bfe_u32 v39, v29, 16, 1
	v_lshrrev_b32_e32 v28, 16, v28
	v_add3_u32 v29, v29, v39, s4
	v_and_or_b32 v28, v29, s33, v28
	v_bfe_u32 v29, v30, 16, 1
	v_add3_u32 v29, v30, v29, s4
	v_bfe_u32 v30, v31, 16, 1
	v_lshlrev_b64 v[36:37], 11, v[78:79]
	v_lshrrev_b32_e32 v29, 16, v29
	v_add3_u32 v30, v31, v30, s4
	v_lshl_add_u64 v[36:37], v[34:35], 0, v[36:37]
	v_and_or_b32 v29, v30, s33, v29
	v_pk_mul_f32 v[24:25], v[24:25], v[32:33] op_sel_hi:[1,0]
	global_store_dwordx2 v[36:37], v[28:29], off
	v_bfe_u32 v28, v24, 16, 1
	v_add3_u32 v24, v24, v28, s4
	v_bfe_u32 v28, v25, 16, 1
	v_pk_mul_f32 v[26:27], v[26:27], v[32:33] op_sel_hi:[1,0]
	v_lshrrev_b32_e32 v24, 16, v24
	v_add3_u32 v25, v25, v28, s4
	v_and_or_b32 v24, v25, s33, v24
	v_bfe_u32 v25, v26, 16, 1
	v_add3_u32 v25, v26, v25, s4
	v_bfe_u32 v26, v27, 16, 1
	v_lshrrev_b32_e32 v25, 16, v25
	v_add3_u32 v26, v27, v26, s4
	v_and_or_b32 v25, v26, s33, v25
	v_pk_mul_f32 v[20:21], v[20:21], v[32:33] op_sel_hi:[1,0]
	global_store_dwordx2 v[36:37], v[24:25], off offset:32
	v_bfe_u32 v24, v20, 16, 1
	v_add3_u32 v20, v20, v24, s4
	v_bfe_u32 v24, v21, 16, 1
	v_mfma_f32_16x16x32_bf16 v[16:19], v[106:109], v[16:19], v[58:61]
	v_mul_f32_e64 v22, v22, v32
	v_mul_f32_e64 v23, v23, v32
	v_lshrrev_b32_e32 v20, 16, v20
	v_add3_u32 v21, v21, v24, s4
	v_and_or_b32 v20, v21, s33, v20
	v_bfe_u32 v21, v22, 16, 1
	v_add3_u32 v21, v22, v21, s4
	v_bfe_u32 v22, v23, 16, 1
	v_lshrrev_b32_e32 v21, 16, v21
	v_add3_u32 v22, v23, v22, s4
	v_and_or_b32 v21, v22, s33, v21
	v_pk_mul_f32 v[16:17], v[16:17], v[32:33] op_sel_hi:[1,0]
	global_store_dwordx2 v[36:37], v[20:21], off offset:64
	v_bfe_u32 v20, v16, 16, 1
	v_add3_u32 v16, v16, v20, s4
	v_bfe_u32 v20, v17, 16, 1
	v_pk_mul_f32 v[18:19], v[18:19], v[32:33] op_sel_hi:[1,0]
	v_lshrrev_b32_e32 v16, 16, v16
	v_add3_u32 v17, v17, v20, s4
	v_and_or_b32 v16, v17, s33, v16
	v_bfe_u32 v17, v18, 16, 1
	v_add3_u32 v17, v18, v17, s4
	v_bfe_u32 v18, v19, 16, 1
	v_lshrrev_b32_e32 v17, 16, v17
	v_add3_u32 v18, v19, v18, s4
	v_and_or_b32 v17, v18, s33, v17
	global_store_dwordx2 v[36:37], v[16:17], off offset:96
	ds_bpermute_b32 v16, v114, v38
	v_mfma_f32_16x16x32_bf16 v[0:3], v[94:97], v[4:7], v[0:3]
	s_waitcnt lgkmcnt(0)
	v_add_f32_e32 v16, v38, v16
	ds_bpermute_b32 v17, v113, v16
	v_mfma_f32_16x16x32_bf16 v[4:7], v[46:49], v[50:53], v[54:57]
	s_waitcnt lgkmcnt(0)
	v_add_f32_e32 v16, v16, v17
	v_div_scale_f32 v17, s[0:1], v16, v16, 1.0
	v_rcp_f32_e32 v18, v17
	v_mfma_f32_16x16x32_bf16 v[0:3], v[106:109], v[50:53], v[0:3]
	v_fma_f32 v19, -v17, v18, 1.0
	v_fmac_f32_e32 v18, v19, v18
	v_div_scale_f32 v19, vcc, 1.0, v16, 1.0
	v_mul_f32_e32 v20, v19, v18
	v_fma_f32 v21, -v17, v20, v19
	v_fmac_f32_e32 v20, v21, v18
	v_fma_f32 v17, -v17, v20, v19
	v_div_fmas_f32 v17, v17, v18, v20
	v_div_fixup_f32 v16, v17, v16, 1.0
	v_pk_mul_f32 v[12:13], v[12:13], v[16:17] op_sel_hi:[1,0]
	v_pk_mul_f32 v[14:15], v[14:15], v[16:17] op_sel_hi:[1,0]
	v_bfe_u32 v17, v12, 16, 1
	v_add3_u32 v12, v12, v17, s4
	v_bfe_u32 v17, v13, 16, 1
	v_lshrrev_b32_e32 v12, 16, v12
	v_add3_u32 v13, v13, v17, s4
	v_and_or_b32 v12, v13, s33, v12
	v_bfe_u32 v13, v14, 16, 1
	v_add3_u32 v13, v14, v13, s4
	v_bfe_u32 v14, v15, 16, 1
	v_lshlrev_b64 v[18:19], 11, v[80:81]
	v_lshrrev_b32_e32 v13, 16, v13
	v_add3_u32 v14, v15, v14, s4
	v_lshl_add_u64 v[18:19], v[34:35], 0, v[18:19]
	v_and_or_b32 v13, v14, s33, v13
	v_pk_mul_f32 v[8:9], v[8:9], v[16:17] op_sel_hi:[1,0]
	global_store_dwordx2 v[18:19], v[12:13], off
	v_bfe_u32 v12, v8, 16, 1
	v_add3_u32 v8, v8, v12, s4
	v_bfe_u32 v12, v9, 16, 1
	v_pk_mul_f32 v[10:11], v[10:11], v[16:17] op_sel_hi:[1,0]
	v_lshrrev_b32_e32 v8, 16, v8
	v_add3_u32 v9, v9, v12, s4
	v_and_or_b32 v8, v9, s33, v8
	v_bfe_u32 v9, v10, 16, 1
	v_add3_u32 v9, v10, v9, s4
	v_bfe_u32 v10, v11, 16, 1
	v_lshrrev_b32_e32 v9, 16, v9
	v_add3_u32 v10, v11, v10, s4
	v_and_or_b32 v9, v10, s33, v9
	v_pk_mul_f32 v[4:5], v[4:5], v[16:17] op_sel_hi:[1,0]
	global_store_dwordx2 v[18:19], v[8:9], off offset:32
	v_bfe_u32 v8, v4, 16, 1
	v_add3_u32 v4, v4, v8, s4
	v_bfe_u32 v8, v5, 16, 1
	v_pk_mul_f32 v[6:7], v[6:7], v[16:17] op_sel_hi:[1,0]
	v_lshrrev_b32_e32 v4, 16, v4
	v_add3_u32 v5, v5, v8, s4
	v_and_or_b32 v4, v5, s33, v4
	v_bfe_u32 v5, v6, 16, 1
	v_add3_u32 v5, v6, v5, s4
	v_bfe_u32 v6, v7, 16, 1
	v_lshrrev_b32_e32 v5, 16, v5
	v_add3_u32 v6, v7, v6, s4
	v_and_or_b32 v5, v6, s33, v5
	v_pk_mul_f32 v[0:1], v[0:1], v[16:17] op_sel_hi:[1,0]
	global_store_dwordx2 v[18:19], v[4:5], off offset:64
	v_bfe_u32 v4, v0, 16, 1
	v_add3_u32 v0, v0, v4, s4
	v_bfe_u32 v4, v1, 16, 1
	v_pk_mul_f32 v[2:3], v[2:3], v[16:17] op_sel_hi:[1,0]
	v_lshrrev_b32_e32 v0, 16, v0
	v_add3_u32 v1, v1, v4, s4
	v_and_or_b32 v0, v1, s33, v0
	v_bfe_u32 v1, v2, 16, 1
	v_add3_u32 v1, v2, v1, s4
	v_bfe_u32 v2, v3, 16, 1
	v_lshrrev_b32_e32 v1, 16, v1
	v_add3_u32 v2, v3, v2, s4
	v_and_or_b32 v1, v2, s33, v1
	global_store_dwordx2 v[18:19], v[0:1], off offset:96
	s_cbranch_scc1 .LBB0_199

.LBB0_189:
	s_or_b64 exec, exec, s[24:25]
	v_ashrrev_i32_e32 v93, 3, v70
	v_add_u32_e32 v20, s12, v93
	v_mov_b64_e32 v[16:17], s[16:17]
	v_and_b32_e32 v15, 7, v70
	v_mad_i64_i32 v[16:17], s[12:13], v20, s26, v[16:17]
	v_lshl_add_u64 v[16:17], v[16:17], 0, s[94:95]
	v_lshlrev_b32_e32 v84, 4, v15
	v_mov_b32_e32 v85, v33
	v_lshl_add_u64 v[16:17], v[16:17], 0, v[84:85]
	global_load_dwordx4 v[20:23], v[16:17], off offset:128
	s_movk_i32 s12, 0xd0
	v_mul_lo_u32 v115, v83, s12
	v_lshlrev_b32_e32 v116, 4, v64
	v_add3_u32 v16, 0, v115, v116
	v_lshlrev_b32_e32 v117, 4, v14
	s_waitcnt vmcnt(1)
	ds_write_b128 v16, v[0:3]
	s_and_saveexec_b64 s[12:13], s[0:1]
	s_xor_b64 s[0:1], exec, s[12:13]
	v_lshlrev_b32_e32 v117, 4, v14
	s_or_saveexec_b64 s[0:1], s[0:1]
	s_movk_i32 s12, 0xd0
	v_mul_lo_u32 v118, v92, s12
	s_xor_b64 exec, exec, s[0:1]
	v_add3_u32 v0, 0, v118, v117
	ds_write_b128 v0, v[4:7]
	s_or_b64 exec, exec, s[0:1]
	s_waitcnt lgkmcnt(1)
	v_add_f32_e32 v0, v67, v68
	s_mov_b32 s12, 0xf800000
	v_mul_f32_e32 v2, 0x4f800000, v0
	v_cmp_gt_f32_e64 s[0:1], s12, v0
	v_or_b32_sdwa v18, v24, v18 dst_sel:DWORD dst_unused:UNUSED_PAD src0_sel:WORD_1 src1_sel:DWORD
	v_or_b32_sdwa v19, v25, v19 dst_sel:DWORD dst_unused:UNUSED_PAD src0_sel:DWORD src1_sel:WORD_1
	v_cndmask_b32_e64 v2, v0, v2, s[0:1]
	v_sqrt_f32_e32 v3, v2
	v_lshlrev_b32_e32 v1, 3, v15
	v_or_b32_sdwa v15, v35, v31 dst_sel:DWORD dst_unused:UNUSED_PAD src0_sel:DWORD src1_sel:WORD_1
	v_mov_b32_e32 v31, 0x260
	v_add_u32_e32 v24, -1, v3
	v_fma_f32 v25, -v24, v3, v2
	v_cmp_ge_f32_e64 s[38:39], 0, v25
	v_add_u32_e32 v25, 1, v3
	v_or_b32_sdwa v16, v12, v8 dst_sel:DWORD dst_unused:UNUSED_PAD src0_sel:WORD_1 src1_sel:DWORD
	v_cndmask_b32_e64 v24, v3, v24, s[38:39]
	v_fma_f32 v3, -v25, v3, v2
	v_cmp_lt_f32_e64 s[38:39], 0, v3
	v_or_b32_sdwa v12, v28, v26 dst_sel:DWORD dst_unused:UNUSED_PAD src0_sel:WORD_1 src1_sel:DWORD
	v_or_b32_sdwa v17, v13, v9 dst_sel:DWORD dst_unused:UNUSED_PAD src0_sel:DWORD src1_sel:WORD_1
	v_cndmask_b32_e64 v3, v24, v25, s[38:39]
	v_mul_f32_e32 v24, 0x37800000, v3
	v_cndmask_b32_e64 v3, v3, v24, s[0:1]
	v_cmp_class_f32_e64 s[0:1], v2, v31
	v_or_b32_sdwa v13, v29, v27 dst_sel:DWORD dst_unused:UNUSED_PAD src0_sel:DWORD src1_sel:WORD_1
	v_or_b32_sdwa v14, v34, v30 dst_sel:DWORD dst_unused:UNUSED_PAD src0_sel:WORD_1 src1_sel:DWORD
	v_cndmask_b32_e64 v2, v3, v2, s[0:1]
	v_add_f32_e32 v3, v77, v82
	v_mul_f32_e32 v24, 0x4f800000, v3
	v_cmp_gt_f32_e64 s[0:1], s12, v3
	s_movk_i32 s12, 0x90
	v_mul_lo_u32 v120, v93, s12
	v_cndmask_b32_e64 v3, v3, v24, s[0:1]
	v_sqrt_f32_e32 v28, v3
	v_lshlrev_b32_e32 v85, 2, v72
	v_or_b32_sdwa v11, v66, v11 dst_sel:DWORD dst_unused:UNUSED_PAD src0_sel:WORD_1 src1_sel:DWORD
	v_mov_b32_e32 v0, 0
	v_add_u32_e32 v29, -1, v28
	v_fma_f32 v30, -v29, v28, v3
	v_cmp_ge_f32_e64 s[38:39], 0, v30
	v_add_u32_e32 v30, 1, v28
	v_mul_f32_e64 v66, v112, -v2
	v_cndmask_b32_e64 v29, v28, v29, s[38:39]
	v_fma_f32 v28, -v30, v28, v3
	v_cmp_lt_f32_e64 s[38:39], 0, v28
	v_lshlrev_b32_e32 v2, 1, v1
	v_or_b32_sdwa v10, v65, v10 dst_sel:DWORD dst_unused:UNUSED_PAD src0_sel:WORD_1 src1_sel:DWORD
	v_cndmask_b32_e64 v28, v29, v30, s[38:39]
	v_mul_f32_e32 v29, 0x37800000, v28
	v_cndmask_b32_e64 v28, v28, v29, s[0:1]
	v_cmp_class_f32_e64 s[0:1], v3, v31
	v_or_b32_sdwa v9, v52, v51 dst_sel:DWORD dst_unused:UNUSED_PAD src0_sel:WORD_1 src1_sel:DWORD
	v_or_b32_sdwa v8, v53, v50 dst_sel:DWORD dst_unused:UNUSED_PAD src0_sel:WORD_1 src1_sel:DWORD
	v_cndmask_b32_e64 v3, v28, v3, s[0:1]
	v_add3_u32 v28, 0, v120, v84
	s_add_u32 s0, s16, s94
	s_waitcnt vmcnt(0)
	ds_write_b128 v28, v[20:23] offset:13312
	s_addc_u32 s1, s17, 0
	v_lshrrev_b32_e32 v20, 2, v71
	v_lshlrev_b32_e32 v21, 3, v70
	v_or_b32_e32 v20, v85, v20
	v_and_b32_e32 v21, 24, v21
	s_lshl_b32 s9, s9, 9
	v_lshl_add_u64 v[88:89], v[62:63], 1, s[0:1]
	v_mul_f32_e64 v62, v112, -v3
	v_mov_b32_e32 v3, v33
	v_or_b32_sdwa v51, v41, v39 dst_sel:DWORD dst_unused:UNUSED_PAD src0_sel:DWORD src1_sel:WORD_1
	v_or_b32_sdwa v50, v40, v38 dst_sel:DWORD dst_unused:UNUSED_PAD src0_sel:WORD_1 src1_sel:DWORD
	v_or_b32_sdwa v53, v45, v43 dst_sel:DWORD dst_unused:UNUSED_PAD src0_sel:DWORD src1_sel:WORD_1
	v_or_b32_sdwa v52, v44, v42 dst_sel:DWORD dst_unused:UNUSED_PAD src0_sel:WORD_1 src1_sel:DWORD
	v_or_b32_sdwa v47, v49, v47 dst_sel:DWORD dst_unused:UNUSED_PAD src0_sel:DWORD src1_sel:WORD_1
	v_or_b32_sdwa v46, v48, v46 dst_sel:DWORD dst_unused:UNUSED_PAD src0_sel:WORD_1 src1_sel:DWORD
	v_or_b32_sdwa v49, v57, v55 dst_sel:DWORD dst_unused:UNUSED_PAD src0_sel:DWORD src1_sel:WORD_1
	v_or_b32_sdwa v48, v56, v54 dst_sel:DWORD dst_unused:UNUSED_PAD src0_sel:WORD_1 src1_sel:DWORD
	v_or_b32_sdwa v27, v76, v61 dst_sel:DWORD dst_unused:UNUSED_PAD src0_sel:WORD_1 src1_sel:DWORD
	v_or_b32_sdwa v26, v75, v60 dst_sel:DWORD dst_unused:UNUSED_PAD src0_sel:WORD_1 src1_sel:DWORD
	v_or_b32_sdwa v25, v73, v59 dst_sel:DWORD dst_unused:UNUSED_PAD src0_sel:WORD_1 src1_sel:DWORD
	v_or_b32_sdwa v24, v74, v58 dst_sel:DWORD dst_unused:UNUSED_PAD src0_sel:WORD_1 src1_sel:DWORD
	v_lshl_add_u64 v[86:87], v[36:37], 1, s[0:1]
	v_mad_u32_u24 v119, v20, s12, v21
	s_addk_i32 s9, 0x5000
	v_mul_u32_u24_e32 v121, 0xd0, v71
	v_mov_b32_e32 v63, v62
	v_mov_b32_e32 v64, v62
	v_mov_b32_e32 v65, v62
	v_mov_b32_e32 v67, v66
	v_mov_b32_e32 v68, v66
	v_mov_b32_e32 v69, v66
	v_lshl_add_u64 v[90:91], s[0:1], 0, v[2:3]
	s_add_i32 s8, s8, 1
	v_add_u32_e32 v122, 64, v92
	v_add_u32_e32 v123, 64, v93
	v_add_u32_e32 v124, 64, v83
	s_mov_b32 s12, 0
	v_mov_b32_e32 v1, v0
	v_mov_b32_e32 v2, v0
	v_mov_b32_e32 v3, v0
	v_mov_b32_e32 v20, v0
	v_mov_b32_e32 v21, v0
	v_mov_b32_e32 v22, v0
	v_mov_b32_e32 v23, v0
	v_mov_b32_e32 v28, v0
	v_mov_b32_e32 v29, v0
	v_mov_b32_e32 v30, v0
	v_mov_b32_e32 v31, v0
	v_mov_b32_e32 v34, v0
	v_mov_b32_e32 v35, v0
	v_mov_b32_e32 v36, v0
	v_mov_b32_e32 v37, v0
	v_mov_b32_e32 v38, v0
	v_mov_b32_e32 v39, v0
	v_mov_b32_e32 v40, v0
	v_mov_b32_e32 v41, v0
	v_mov_b32_e32 v42, v0
	v_mov_b32_e32 v43, v0
	v_mov_b32_e32 v44, v0
	v_mov_b32_e32 v45, v0
	v_mov_b32_e32 v54, v0
	v_mov_b32_e32 v55, v0
	v_mov_b32_e32 v56, v0
	v_mov_b32_e32 v57, v0
	v_mov_b32_e32 v58, v0
	v_mov_b32_e32 v59, v0
	v_mov_b32_e32 v60, v0
	v_mov_b32_e32 v61, v0
	v_mov_b32_e32 v82, v0
	v_mov_b32_e32 v83, v0
	s_waitcnt lgkmcnt(0)
	s_barrier
	s_cbranch_vccnz .Lprio_done
	s_setprio 1
.Lprio_done:
	s_branch .LBB0_195
.LBB0_194:
	s_or_b64 exec, exec, s[0:1]
	v_add_f32_e32 v74, 0, v125
	v_add_f32_e32 v74, v126, v74
	v_add_f32_e32 v74, v127, v74
	v_add_f32_e32 v74, v128, v74
	v_add_f32_e32 v74, v129, v74
	v_add_f32_e32 v75, v130, v74
	v_add_f32_e32 v74, 0, v131
	v_add_f32_e32 v74, v132, v74
	v_add_f32_e32 v74, v133, v74
	v_add_f32_e32 v74, v134, v74
	v_add_f32_e32 v74, v135, v74
	v_add_f32_e32 v74, v136, v74
	v_pk_add_f32 v[74:75], v[110:111], v[74:75]
	v_add_u32_e32 v122, 64, v122
	v_pk_add_f32 v[74:75], v[108:109], v[74:75]
	v_add_u32_e32 v123, 64, v123
	v_pk_add_f32 v[74:75], v[106:107], v[74:75]
	s_cmp_eq_u32 s8, s12
	v_pk_add_f32 v[74:75], v[104:105], v[74:75]
	v_add_u32_e32 v124, 64, v124
	v_pk_add_f32 v[74:75], v[102:103], v[74:75]
	s_nop 0
	v_pk_add_f32 v[74:75], v[100:101], v[74:75]
	s_nop 0
	v_pk_add_f32 v[74:75], v[98:99], v[74:75]
	s_nop 0
	v_pk_add_f32 v[74:75], v[96:97], v[74:75]
	s_nop 0
	v_pk_add_f32 v[74:75], v[94:95], v[74:75]
	s_nop 0
	v_pk_add_f32 v[74:75], v[92:93], v[74:75]
	s_nop 0
	v_pk_add_f32 v[82:83], v[82:83], v[74:75]
	v_add3_u32 v74, s13, v120, v84
	s_waitcnt vmcnt(0)
	ds_write_b128 v74, v[70:73] offset:13312
	s_waitcnt lgkmcnt(0)
	s_barrier
	s_cbranch_scc1 .LBB0_178
